# NA: gate loads of block 0 issued before the last iteration, next tile loads issued right after the tile store
# speedup vs baseline: 1.0143x; 1.0029x over previous
.Lna_tb_done0:
	s_lshl_b32 s1, s1, 15
	s_lshl_b32 s2, s43, 8
	s_add_u32 s1, s1, s2
	s_add_u32 s1, s1, 0x2000
	s_add_u32 s54, s26, s1
	s_addc_u32 s55, s27, 0
	s_add_u32 s56, s54, 0x2000
	s_addc_u32 s57, s55, 0
	global_load_dwordx4 v[96:99], v194, s[54:55]
	global_load_dwordx4 v[100:103], v194, s[56:57]
	global_load_dwordx4 v[104:107], v195, s[54:55]
	global_load_dwordx4 v[108:111], v195, s[56:57]
	s_lshl_b32 s6, s43, 8
	s_lshl_b32 s7, s8, 15
	s_add_u32 s7, s7, s6
	s_add_u32 s7, s7, 0x6000
	s_add_u32 s72, s26, s7
	s_addc_u32 s73, s27, 0
	s_lshl_b32 s7, s8, 13
	s_add_u32 s7, s7, s6
	s_add_u32 s12, s28, s7
	s_addc_u32 s13, s29, 0
	s_lshl_b32 s7, s9, 15
	s_add_u32 s7, s7, s6
	s_add_u32 s7, s7, 0x6000
	s_add_u32 s16, s26, s7
	s_addc_u32 s17, s27, 0
	s_lshl_b32 s7, s9, 13
	s_add_u32 s7, s7, s6
	s_add_u32 s30, s28, s7
	s_addc_u32 s31, s29, 0
	v_mov_b64_e32 v[0:1], 0
	v_mov_b64_e32 v[2:3], 0
	v_mov_b64_e32 v[4:5], 0
	v_mov_b64_e32 v[6:7], 0
	v_mov_b64_e32 v[8:9], 0
	v_mov_b64_e32 v[10:11], 0
	v_mov_b64_e32 v[12:13], 0
	v_mov_b64_e32 v[14:15], 0
	v_mov_b64_e32 v[16:17], 0
	v_mov_b64_e32 v[18:19], 0
	v_mov_b64_e32 v[20:21], 0
	v_mov_b64_e32 v[22:23], 0
	v_mov_b64_e32 v[24:25], 0
	v_mov_b64_e32 v[26:27], 0
	v_mov_b64_e32 v[28:29], 0
	v_mov_b64_e32 v[30:31], 0
	v_mov_b64_e32 v[32:33], 0
	v_mov_b64_e32 v[34:35], 0
	v_mov_b64_e32 v[36:37], 0
	v_mov_b64_e32 v[38:39], 0
	v_mov_b64_e32 v[40:41], 0
	v_mov_b64_e32 v[42:43], 0
	v_mov_b64_e32 v[44:45], 0
	v_mov_b64_e32 v[46:47], 0
	v_mov_b64_e32 v[48:49], 0
	v_mov_b64_e32 v[50:51], 0
	v_mov_b64_e32 v[52:53], 0
	v_mov_b64_e32 v[54:55], 0
	v_mov_b64_e32 v[56:57], 0
	v_mov_b64_e32 v[58:59], 0
	v_mov_b64_e32 v[60:61], 0
	v_mov_b64_e32 v[62:63], 0
	v_mov_b32_e32 v218, 0xf149f2ca
	v_mov_b32_e32 v221, 0xf149f2ca
	v_mov_b32_e32 v219, 0xf149f2ca
	v_mov_b32_e32 v222, 0xf149f2ca
	v_mov_b32_e32 v220, 0
	v_mov_b32_e32 v223, 0
	s_waitcnt vmcnt(4)
	v_mul_f32_e32 v236, 0x3fb8aa3b, v236
	v_cndmask_b32_e64 v236, v247, v236, s[22:23]
	ds_write_b32 v214, v236
	s_waitcnt vmcnt(0)
	v_mov_b32_e32 v234, v196
	v_mov_b32_e32 v235, v197
	ds_write_b128 v234, v[96:99]
	ds_write_b128 v235, v[100:103]
	ds_write_b128 v234, v[104:107] offset:9216
	ds_write_b128 v235, v[108:111] offset:9216
	s_waitcnt lgkmcnt(0)
	s_mov_b32 s11, 1
	s_cmp_lt_u32 s11, s50
	s_cbranch_scc0 .Lna_tb_ctx1
	s_add_u32 s1, s49, s11
	s_lshl_b32 s1, s1, 6
	s_lshl_b32 s2, s42, 11
	s_add_u32 s1, s1, s2
	s_branch .Lna_tb_done1

.Lna_tb_done1:
	s_lshl_b32 s1, s1, 15
	s_lshl_b32 s2, s43, 8
	s_add_u32 s1, s1, s2
	s_add_u32 s1, s1, 0x2000
	s_add_u32 s54, s26, s1
	s_addc_u32 s55, s27, 0
	s_add_u32 s56, s54, 0x2000
	s_addc_u32 s57, s55, 0
	global_load_dwordx4 v[96:99], v194, s[54:55]
	global_load_dwordx4 v[100:103], v194, s[56:57]
	global_load_dwordx4 v[104:107], v195, s[54:55]
	global_load_dwordx4 v[108:111], v195, s[56:57]
	s_waitcnt lgkmcnt(0)
	s_barrier
	s_branch .Lna_itloop
.Lna_unit_next:
	s_lshl_b32 s6, s43, 8
	s_lshl_b32 s7, s8, 15
	s_add_u32 s7, s7, s6
	s_add_u32 s7, s7, 0x6000
	s_add_u32 s72, s26, s7
	s_addc_u32 s73, s27, 0
	s_lshl_b32 s7, s8, 13
	s_add_u32 s7, s7, s6
	s_add_u32 s12, s28, s7
	s_addc_u32 s13, s29, 0
	s_lshl_b32 s7, s9, 15
	s_add_u32 s7, s7, s6
	s_add_u32 s7, s7, 0x6000
	s_add_u32 s16, s26, s7
	s_addc_u32 s17, s27, 0
	s_lshl_b32 s7, s9, 13
	s_add_u32 s7, s7, s6
	s_add_u32 s30, s28, s7
	s_addc_u32 s31, s29, 0
	v_mov_b64_e32 v[0:1], 0
	v_mov_b64_e32 v[2:3], 0
	v_mov_b64_e32 v[4:5], 0
	v_mov_b64_e32 v[6:7], 0
	v_mov_b64_e32 v[8:9], 0
	v_mov_b64_e32 v[10:11], 0
	v_mov_b64_e32 v[12:13], 0
	v_mov_b64_e32 v[14:15], 0
	v_mov_b64_e32 v[16:17], 0
	v_mov_b64_e32 v[18:19], 0
	v_mov_b64_e32 v[20:21], 0
	v_mov_b64_e32 v[22:23], 0
	v_mov_b64_e32 v[24:25], 0
	v_mov_b64_e32 v[26:27], 0
	v_mov_b64_e32 v[28:29], 0
	v_mov_b64_e32 v[30:31], 0
	v_mov_b64_e32 v[32:33], 0
	v_mov_b64_e32 v[34:35], 0
	v_mov_b64_e32 v[36:37], 0
	v_mov_b64_e32 v[38:39], 0
	v_mov_b64_e32 v[40:41], 0
	v_mov_b64_e32 v[42:43], 0
	v_mov_b64_e32 v[44:45], 0
	v_mov_b64_e32 v[46:47], 0
	v_mov_b64_e32 v[48:49], 0
	v_mov_b64_e32 v[50:51], 0
	v_mov_b64_e32 v[52:53], 0
	v_mov_b64_e32 v[54:55], 0
	v_mov_b64_e32 v[56:57], 0
	v_mov_b64_e32 v[58:59], 0
	v_mov_b64_e32 v[60:61], 0
	v_mov_b64_e32 v[62:63], 0
	v_mov_b32_e32 v218, 0xf149f2ca
	v_mov_b32_e32 v221, 0xf149f2ca
	v_mov_b32_e32 v219, 0xf149f2ca
	v_mov_b32_e32 v222, 0xf149f2ca
	v_mov_b32_e32 v220, 0
	v_mov_b32_e32 v223, 0
	s_waitcnt vmcnt(12)
	v_mul_f32_e32 v236, 0x3fb8aa3b, v236
	v_cndmask_b32_e64 v236, v247, v236, s[22:23]
	ds_write_b32 v214, v236
	s_waitcnt vmcnt(4)
	v_mov_b32_e32 v234, v196
	v_mov_b32_e32 v235, v197
	ds_write_b128 v234, v[96:99]
	ds_write_b128 v235, v[100:103]
	ds_write_b128 v234, v[104:107] offset:9216
	ds_write_b128 v235, v[108:111] offset:9216
	s_waitcnt lgkmcnt(0)
	s_mov_b32 s11, 1
	s_cmp_lt_u32 s11, s50
	s_cbranch_scc0 .Lna_tb_ctx2
	s_add_u32 s1, s49, s11
	s_lshl_b32 s1, s1, 6
	s_lshl_b32 s2, s42, 11
	s_add_u32 s1, s1, s2
	s_branch .Lna_tb_done2

.Lna_tb_done2:
	s_lshl_b32 s1, s1, 15
	s_lshl_b32 s2, s43, 8
	s_add_u32 s1, s1, s2
	s_add_u32 s1, s1, 0x2000
	s_add_u32 s54, s26, s1
	s_addc_u32 s55, s27, 0
	s_add_u32 s56, s54, 0x2000
	s_addc_u32 s57, s55, 0
	global_load_dwordx4 v[96:99], v194, s[54:55]
	global_load_dwordx4 v[100:103], v194, s[56:57]
	global_load_dwordx4 v[104:107], v195, s[54:55]
	global_load_dwordx4 v[108:111], v195, s[56:57]
	s_waitcnt lgkmcnt(0)
	s_barrier

.Lna_nostag:
	s_add_u32 s11, s52, 1
	s_cmp_lt_u32 s11, s51
	s_cselect_b32 s67, 1, 0
	s_cmp_lt_u32 s52, s50
	s_cbranch_scc0 .Lna_ctx
	s_add_u32 s1, s49, s52
	s_sub_u32 s2, s1, s47
	s_cmp_lt_u32 s2, 8
	s_cselect_b32 s4, 1, 0
	s_sub_u32 s2, s1, s48
	s_cmp_lt_u32 s2, 8
	s_cselect_b32 s5, 1, 0
	s_or_b32 s6, s4, s5
	s_cmp_eq_u32 s6, 0
	s_cbranch_scc1 .Lna_endcompute
	s_sub_u32 s2, s1, s46
	s_add_u32 s2, s2, 7
	s_cmp_eq_u32 s4, 1
	s_cselect_b32 s6, s2, 15
	s_lshl_b32 s6, s6, 7
	s_add_u32 s78, s6, 0x12000
	s_sub_u32 s2, s2, 1
	s_cmp_eq_u32 s5, 1
	s_cselect_b32 s6, s2, 15
	s_lshl_b32 s6, s6, 7
	s_add_u32 s79, s6, 0x12000
	v_add_u32_e32 v232, s66, v198
	v_add_u32_e32 v233, s66, v200
	ds_read_b128 v[112:115], v232 offset:0
	ds_read_b128 v[116:119], v232 offset:4608
	ds_read_b128 v[120:123], v232 offset:64
	ds_read_b128 v[124:127], v232 offset:4672
	ds_read_b128 v[128:131], v232 offset:128
	ds_read_b128 v[132:135], v232 offset:4736
	ds_read_b128 v[136:139], v232 offset:192
	ds_read_b128 v[140:143], v232 offset:4800
	s_waitcnt lgkmcnt(6)
	v_mfma_f32_16x16x32_bf16 v[144:147], v[112:115], v[64:67], 0
	v_mfma_f32_16x16x32_bf16 v[148:151], v[116:119], v[64:67], 0
	v_add_u32_e32 v160, s78, v202
	ds_read_b32 v160, v160
	v_add_u32_e32 v161, s78, v203
	ds_read_b32 v161, v161
	v_add_u32_e32 v162, s78, v204
	ds_read_b32 v162, v162
	v_add_u32_e32 v163, s78, v205
	ds_read_b32 v163, v163
	v_add_u32_e32 v164, s78, v206
	ds_read_b32 v164, v164
	v_add_u32_e32 v165, s78, v207
	ds_read_b32 v165, v165
	v_add_u32_e32 v166, s78, v208
	ds_read_b32 v166, v166
	v_add_u32_e32 v167, s78, v209
	ds_read_b32 v167, v167
	s_waitcnt lgkmcnt(12)
	v_mfma_f32_16x16x32_bf16 v[144:147], v[120:123], v[68:71], v[144:147]
	v_mfma_f32_16x16x32_bf16 v[148:151], v[124:127], v[68:71], v[148:151]
	s_waitcnt lgkmcnt(10)
	v_mfma_f32_16x16x32_bf16 v[144:147], v[128:131], v[72:75], v[144:147]
	v_mfma_f32_16x16x32_bf16 v[148:151], v[132:135], v[72:75], v[148:151]
	s_waitcnt lgkmcnt(8)
	v_mfma_f32_16x16x32_bf16 v[144:147], v[136:139], v[76:79], v[144:147]
	v_mfma_f32_16x16x32_bf16 v[148:151], v[140:143], v[76:79], v[148:151]
	s_waitcnt lgkmcnt(0)
	v_add_u32_e32 v179, s79, v202
	ds_read_b32 v179, v179
	v_add_u32_e32 v180, s79, v203
	ds_read_b32 v180, v180
	v_add_u32_e32 v181, s79, v204
	ds_read_b32 v181, v181
	v_add_u32_e32 v182, s79, v205
	ds_read_b32 v182, v182
	v_add_u32_e32 v183, s79, v206
	ds_read_b32 v183, v183
	v_add_u32_e32 v184, s79, v207
	ds_read_b32 v184, v184
	v_add_u32_e32 v185, s79, v208
	ds_read_b32 v185, v185
	v_add_u32_e32 v186, s79, v209
	ds_read_b32 v186, v186
	v_mfma_f32_16x16x32_bf16 v[152:155], v[112:115], v[80:83], 0
	v_mfma_f32_16x16x32_bf16 v[156:159], v[116:119], v[80:83], 0
	ds_read_b64_tr_b16 v[112:113], v233 offset:0
	ds_read_b64_tr_b16 v[114:115], v233 offset:4608
	ds_read_b64_tr_b16 v[116:117], v233 offset:32
	ds_read_b64_tr_b16 v[118:119], v233 offset:4640
	v_fma_f32 v160, v144, s53, v160
	v_fma_f32 v161, v145, s53, v161
	v_fma_f32 v162, v146, s53, v162
	v_fma_f32 v163, v147, s53, v163
	v_fma_f32 v164, v148, s53, v164
	v_fma_f32 v165, v149, s53, v165
	v_fma_f32 v166, v150, s53, v166
	v_fma_f32 v167, v151, s53, v167
	v_max3_f32 v224, v160, v161, v162
	v_max3_f32 v224, v224, v163, v164
	v_mfma_f32_16x16x32_bf16 v[152:155], v[120:123], v[84:87], v[152:155]
	v_mfma_f32_16x16x32_bf16 v[156:159], v[124:127], v[84:87], v[156:159]
	s_waitcnt lgkmcnt(4)
	ds_read_b64_tr_b16 v[120:121], v233 offset:64
	ds_read_b64_tr_b16 v[122:123], v233 offset:4672
	ds_read_b64_tr_b16 v[124:125], v233 offset:96
	ds_read_b64_tr_b16 v[126:127], v233 offset:4704
	v_max3_f32 v224, v224, v165, v166
	v_max_f32_e32 v224, v224, v167
	v_cmp_gt_f32_e32 vcc, v224, v219
	s_cbranch_vccnz .Lna_rare_L_b0

.Lna_endcompute:
	s_cmp_eq_u32 s67, 0
	s_cbranch_scc1 .Lna_nostore
	s_sub_u32 s1, 0x9000, s66
	v_add_u32_e32 v234, s1, v196
	v_add_u32_e32 v235, s1, v197
	s_waitcnt vmcnt(0)
	ds_write_b128 v234, v[96:99]
	ds_write_b128 v235, v[100:103]
	ds_write_b128 v234, v[104:107] offset:9216
	ds_write_b128 v235, v[108:111] offset:9216
	s_waitcnt lgkmcnt(0)
	s_add_u32 s11, s52, 2
	s_cmp_lt_u32 s11, s51
	s_cbranch_scc0 .Lna_gate0
	s_cmp_lt_u32 s11, s50
	s_cbranch_scc0 .Lna_tb_ctx3
	s_add_u32 s1, s49, s11
	s_lshl_b32 s1, s1, 6
	s_lshl_b32 s2, s42, 11
	s_add_u32 s1, s1, s2
	s_branch .Lna_tb_done3

.Lna_tb_done3:
	s_lshl_b32 s1, s1, 15
	s_lshl_b32 s2, s43, 8
	s_add_u32 s1, s1, s2
	s_add_u32 s1, s1, 0x2000
	s_add_u32 s54, s26, s1
	s_addc_u32 s55, s27, 0
	s_add_u32 s56, s54, 0x2000
	s_addc_u32 s57, s55, 0
	global_load_dwordx4 v[96:99], v194, s[54:55]
	global_load_dwordx4 v[100:103], v194, s[56:57]
	global_load_dwordx4 v[104:107], v195, s[54:55]
	global_load_dwordx4 v[108:111], v195, s[56:57]
	s_branch .Lna_nostore
.Lna_gate0:
	global_load_dwordx4 v[96:99], v211, s[72:73] offset:0
	global_load_dwordx4 v[100:103], v211, s[72:73] offset:64
	global_load_dwordx4 v[104:107], v211, s[72:73] offset:128
	global_load_dwordx4 v[108:111], v211, s[72:73] offset:192
.Lna_nostore:
	s_waitcnt lgkmcnt(0)
	s_barrier
	s_sub_u32 s66, 0x9000, s66
	s_add_u32 s52, s52, 1
	s_cmp_lt_u32 s52, s51
	s_cbranch_scc1 .Lna_it
	global_load_dwordx4 v[128:131], v211, s[16:17] offset:0
	global_load_dwordx4 v[132:135], v211, s[16:17] offset:64
	global_load_dwordx4 v[136:139], v211, s[16:17] offset:128
	global_load_dwordx4 v[140:143], v211, s[16:17] offset:192
	s_add_u32 s15, s40, s94
	s_cmp_lt_u32 s15, s41
	s_cselect_b32 s40, s15, s40
	s_cmp_ge_u32 s40, 0x400
	s_cbranch_scc1 .Lna_dec_ctx_1
	s_mov_b32 s45, 0
	s_cmp_eq_u32 s94, 0x100
	s_cbranch_scc0 .Lna_dec_gen_1
	s_lshr_b32 s1, s40, 8
	s_and_b32 s2, s40, 0xff
	s_lshl_b32 s1, s1, 5
	s_and_b32 s4, s2, 7
	s_lshl_b32 s4, s4, 2
	s_add_u32 s1, s1, s4
	s_lshr_b32 s4, s2, 6
	s_add_u32 s1, s1, s4
	s_bfe_u32 s44, s2, 0x30003
	s_branch .Lna_dec_l2_1

.Lna_dec_done_1:
	s_add_u32 s51, s50, 4
	s_mov_b32 s8, s4
	s_mov_b32 s9, s5
	s_lshl_b32 s6, s43, 8
	s_lshl_b32 s7, s4, 15
	s_add_u32 s7, s7, s6
	s_add_u32 s58, s26, s7
	s_addc_u32 s59, s27, 0
	s_lshl_b32 s7, s5, 15
	s_add_u32 s7, s7, s6
	s_add_u32 s60, s26, s7
	s_addc_u32 s61, s27, 0
	s_mul_i32 s7, s43, 0x744
	s_add_u32 s64, s24, s7
	s_addc_u32 s65, s25, 0
	global_load_dwordx4 v[64:67], v210, s[58:59]
	global_load_dwordx4 v[68:71], v210, s[58:59] offset:64
	global_load_dwordx4 v[72:75], v210, s[58:59] offset:128
	global_load_dwordx4 v[76:79], v210, s[58:59] offset:192
	global_load_dwordx4 v[80:83], v210, s[60:61]
	global_load_dwordx4 v[84:87], v210, s[60:61] offset:64
	global_load_dwordx4 v[88:91], v210, s[60:61] offset:128
	global_load_dwordx4 v[92:95], v210, s[60:61] offset:192
	global_load_dword v236, v213, s[64:65]
	s_mov_b32 s4, 0xbfb8aa3b
	s_mov_b32 s5, 0xbfb8aa3b
	ds_bpermute_b32 v224, v215, v220
	s_waitcnt lgkmcnt(0)
	v_add_f32_e32 v220, v220, v224
	ds_bpermute_b32 v224, v216, v220
	s_waitcnt lgkmcnt(0)
	v_add_f32_e32 v224, v220, v224
	v_mov_b32_e32 v225, v224
	s_waitcnt vmcnt(13)
	v_permlane16_swap_b32_e32 v96, v98
	v_permlane16_swap_b32_e32 v97, v99
	v_lshlrev_b32_e32 v226, 16, v96
	v_and_b32_e32 v227, 0xffff0000, v96
	v_lshlrev_b32_e32 v228, 16, v97
	v_and_b32_e32 v229, 0xffff0000, v97
	v_pk_mul_f32 v[230:231], v[226:227], s[4:5]
	v_pk_mul_f32 v[160:161], v[228:229], s[4:5]
	v_exp_f32_e32 v230, v230
	v_exp_f32_e32 v231, v231
	v_exp_f32_e32 v160, v160
	v_exp_f32_e32 v161, v161
	v_pk_mul_f32 v[0:1], v[0:1], v[226:227]
	v_pk_mul_f32 v[2:3], v[2:3], v[228:229]
	v_pk_fma_f32 v[230:231], v[230:231], v[224:225], v[224:225]
	v_pk_fma_f32 v[160:161], v[160:161], v[224:225], v[224:225]
	v_rcp_f32_e32 v230, v230
	v_rcp_f32_e32 v231, v231
	v_rcp_f32_e32 v160, v160
	v_rcp_f32_e32 v161, v161
	s_nop 0
	v_pk_mul_f32 v[0:1], v[0:1], v[230:231]
	v_pk_mul_f32 v[2:3], v[2:3], v[160:161]
	v_lshlrev_b32_e32 v226, 16, v98
	v_and_b32_e32 v227, 0xffff0000, v98
	v_lshlrev_b32_e32 v228, 16, v99
	v_and_b32_e32 v229, 0xffff0000, v99
	v_pk_mul_f32 v[230:231], v[226:227], s[4:5]
	v_pk_mul_f32 v[160:161], v[228:229], s[4:5]
	v_exp_f32_e32 v230, v230
	v_exp_f32_e32 v231, v231
	v_exp_f32_e32 v160, v160
	v_exp_f32_e32 v161, v161
	v_pk_mul_f32 v[4:5], v[4:5], v[226:227]
	v_pk_mul_f32 v[6:7], v[6:7], v[228:229]
	v_pk_fma_f32 v[230:231], v[230:231], v[224:225], v[224:225]
	v_pk_fma_f32 v[160:161], v[160:161], v[224:225], v[224:225]
	v_rcp_f32_e32 v230, v230
	v_rcp_f32_e32 v231, v231
	v_rcp_f32_e32 v160, v160
	v_rcp_f32_e32 v161, v161
	s_nop 0
	v_pk_mul_f32 v[4:5], v[4:5], v[230:231]
	v_pk_mul_f32 v[6:7], v[6:7], v[160:161]
	v_cvt_pk_bf16_f32 v0, v0, v1
	v_cvt_pk_bf16_f32 v1, v2, v3
	v_cvt_pk_bf16_f32 v2, v4, v5
	v_cvt_pk_bf16_f32 v3, v6, v7
	s_nop 1
	v_permlane16_swap_b32_e32 v0, v2
	v_permlane16_swap_b32_e32 v1, v3
	global_store_dwordx4 v212, v[0:3], s[12:13] offset:0
	v_permlane16_swap_b32_e32 v100, v102
	v_permlane16_swap_b32_e32 v101, v103
	v_lshlrev_b32_e32 v226, 16, v100
	v_and_b32_e32 v227, 0xffff0000, v100
	v_lshlrev_b32_e32 v228, 16, v101
	v_and_b32_e32 v229, 0xffff0000, v101
	v_pk_mul_f32 v[230:231], v[226:227], s[4:5]
	v_pk_mul_f32 v[160:161], v[228:229], s[4:5]
	v_exp_f32_e32 v230, v230
	v_exp_f32_e32 v231, v231
	v_exp_f32_e32 v160, v160
	v_exp_f32_e32 v161, v161
	v_pk_mul_f32 v[8:9], v[8:9], v[226:227]
	v_pk_mul_f32 v[10:11], v[10:11], v[228:229]
	v_pk_fma_f32 v[230:231], v[230:231], v[224:225], v[224:225]
	v_pk_fma_f32 v[160:161], v[160:161], v[224:225], v[224:225]
	v_rcp_f32_e32 v230, v230
	v_rcp_f32_e32 v231, v231
	v_rcp_f32_e32 v160, v160
	v_rcp_f32_e32 v161, v161
	s_nop 0
	v_pk_mul_f32 v[8:9], v[8:9], v[230:231]
	v_pk_mul_f32 v[10:11], v[10:11], v[160:161]
	v_lshlrev_b32_e32 v226, 16, v102
	v_and_b32_e32 v227, 0xffff0000, v102
	v_lshlrev_b32_e32 v228, 16, v103
	v_and_b32_e32 v229, 0xffff0000, v103
	v_pk_mul_f32 v[230:231], v[226:227], s[4:5]
	v_pk_mul_f32 v[160:161], v[228:229], s[4:5]
	v_exp_f32_e32 v230, v230
	v_exp_f32_e32 v231, v231
	v_exp_f32_e32 v160, v160
	v_exp_f32_e32 v161, v161
	v_pk_mul_f32 v[12:13], v[12:13], v[226:227]
	v_pk_mul_f32 v[14:15], v[14:15], v[228:229]
	v_pk_fma_f32 v[230:231], v[230:231], v[224:225], v[224:225]
	v_pk_fma_f32 v[160:161], v[160:161], v[224:225], v[224:225]
	v_rcp_f32_e32 v230, v230
	v_rcp_f32_e32 v231, v231
	v_rcp_f32_e32 v160, v160
	v_rcp_f32_e32 v161, v161
	s_nop 0
	v_pk_mul_f32 v[12:13], v[12:13], v[230:231]
	v_pk_mul_f32 v[14:15], v[14:15], v[160:161]
	v_cvt_pk_bf16_f32 v8, v8, v9
	v_cvt_pk_bf16_f32 v9, v10, v11
	v_cvt_pk_bf16_f32 v10, v12, v13
	v_cvt_pk_bf16_f32 v11, v14, v15
	s_nop 1
	v_permlane16_swap_b32_e32 v8, v10
	v_permlane16_swap_b32_e32 v9, v11
	global_store_dwordx4 v212, v[8:11], s[12:13] offset:64
	v_permlane16_swap_b32_e32 v104, v106
	v_permlane16_swap_b32_e32 v105, v107
	v_lshlrev_b32_e32 v226, 16, v104
	v_and_b32_e32 v227, 0xffff0000, v104
	v_lshlrev_b32_e32 v228, 16, v105
	v_and_b32_e32 v229, 0xffff0000, v105
	v_pk_mul_f32 v[230:231], v[226:227], s[4:5]
	v_pk_mul_f32 v[160:161], v[228:229], s[4:5]
	v_exp_f32_e32 v230, v230
	v_exp_f32_e32 v231, v231
	v_exp_f32_e32 v160, v160
	v_exp_f32_e32 v161, v161
	v_pk_mul_f32 v[16:17], v[16:17], v[226:227]
	v_pk_mul_f32 v[18:19], v[18:19], v[228:229]
	v_pk_fma_f32 v[230:231], v[230:231], v[224:225], v[224:225]
	v_pk_fma_f32 v[160:161], v[160:161], v[224:225], v[224:225]
	v_rcp_f32_e32 v230, v230
	v_rcp_f32_e32 v231, v231
	v_rcp_f32_e32 v160, v160
	v_rcp_f32_e32 v161, v161
	s_nop 0
	v_pk_mul_f32 v[16:17], v[16:17], v[230:231]
	v_pk_mul_f32 v[18:19], v[18:19], v[160:161]
	v_lshlrev_b32_e32 v226, 16, v106
	v_and_b32_e32 v227, 0xffff0000, v106
	v_lshlrev_b32_e32 v228, 16, v107
	v_and_b32_e32 v229, 0xffff0000, v107
	v_pk_mul_f32 v[230:231], v[226:227], s[4:5]
	v_pk_mul_f32 v[160:161], v[228:229], s[4:5]
	v_exp_f32_e32 v230, v230
	v_exp_f32_e32 v231, v231
	v_exp_f32_e32 v160, v160
	v_exp_f32_e32 v161, v161
	v_pk_mul_f32 v[20:21], v[20:21], v[226:227]
	v_pk_mul_f32 v[22:23], v[22:23], v[228:229]
	v_pk_fma_f32 v[230:231], v[230:231], v[224:225], v[224:225]
	v_pk_fma_f32 v[160:161], v[160:161], v[224:225], v[224:225]
	v_rcp_f32_e32 v230, v230
	v_rcp_f32_e32 v231, v231
	v_rcp_f32_e32 v160, v160
	v_rcp_f32_e32 v161, v161
	s_nop 0
	v_pk_mul_f32 v[20:21], v[20:21], v[230:231]
	v_pk_mul_f32 v[22:23], v[22:23], v[160:161]
	v_cvt_pk_bf16_f32 v16, v16, v17
	v_cvt_pk_bf16_f32 v17, v18, v19
	v_cvt_pk_bf16_f32 v18, v20, v21
	v_cvt_pk_bf16_f32 v19, v22, v23
	s_nop 1
	v_permlane16_swap_b32_e32 v16, v18
	v_permlane16_swap_b32_e32 v17, v19
	global_store_dwordx4 v212, v[16:19], s[12:13] offset:128
	v_permlane16_swap_b32_e32 v108, v110
	v_permlane16_swap_b32_e32 v109, v111
	v_lshlrev_b32_e32 v226, 16, v108
	v_and_b32_e32 v227, 0xffff0000, v108
	v_lshlrev_b32_e32 v228, 16, v109
	v_and_b32_e32 v229, 0xffff0000, v109
	v_pk_mul_f32 v[230:231], v[226:227], s[4:5]
	v_pk_mul_f32 v[160:161], v[228:229], s[4:5]
	v_exp_f32_e32 v230, v230
	v_exp_f32_e32 v231, v231
	v_exp_f32_e32 v160, v160
	v_exp_f32_e32 v161, v161
	v_pk_mul_f32 v[24:25], v[24:25], v[226:227]
	v_pk_mul_f32 v[26:27], v[26:27], v[228:229]
	v_pk_fma_f32 v[230:231], v[230:231], v[224:225], v[224:225]
	v_pk_fma_f32 v[160:161], v[160:161], v[224:225], v[224:225]
	v_rcp_f32_e32 v230, v230
	v_rcp_f32_e32 v231, v231
	v_rcp_f32_e32 v160, v160
	v_rcp_f32_e32 v161, v161
	s_nop 0
	v_pk_mul_f32 v[24:25], v[24:25], v[230:231]
	v_pk_mul_f32 v[26:27], v[26:27], v[160:161]
	v_lshlrev_b32_e32 v226, 16, v110
	v_and_b32_e32 v227, 0xffff0000, v110
	v_lshlrev_b32_e32 v228, 16, v111
	v_and_b32_e32 v229, 0xffff0000, v111
	v_pk_mul_f32 v[230:231], v[226:227], s[4:5]
	v_pk_mul_f32 v[160:161], v[228:229], s[4:5]
	v_exp_f32_e32 v230, v230
	v_exp_f32_e32 v231, v231
	v_exp_f32_e32 v160, v160
	v_exp_f32_e32 v161, v161
	v_pk_mul_f32 v[28:29], v[28:29], v[226:227]
	v_pk_mul_f32 v[30:31], v[30:31], v[228:229]
	v_pk_fma_f32 v[230:231], v[230:231], v[224:225], v[224:225]
	v_pk_fma_f32 v[160:161], v[160:161], v[224:225], v[224:225]
	v_rcp_f32_e32 v230, v230
	v_rcp_f32_e32 v231, v231
	v_rcp_f32_e32 v160, v160
	v_rcp_f32_e32 v161, v161
	s_nop 0
	v_pk_mul_f32 v[28:29], v[28:29], v[230:231]
	v_pk_mul_f32 v[30:31], v[30:31], v[160:161]
	v_cvt_pk_bf16_f32 v24, v24, v25
	v_cvt_pk_bf16_f32 v25, v26, v27
	v_cvt_pk_bf16_f32 v26, v28, v29
	v_cvt_pk_bf16_f32 v27, v30, v31
	s_nop 1
	v_permlane16_swap_b32_e32 v24, v26
	v_permlane16_swap_b32_e32 v25, v27
	global_store_dwordx4 v212, v[24:27], s[12:13] offset:192
	ds_bpermute_b32 v224, v215, v223
	s_waitcnt lgkmcnt(0)
	v_add_f32_e32 v223, v223, v224
	ds_bpermute_b32 v224, v216, v223
	s_waitcnt lgkmcnt(0)
	v_add_f32_e32 v224, v223, v224
	v_mov_b32_e32 v225, v224
	s_mov_b32 s52, 0
	s_cmp_lt_u32 s52, s50
	s_cbranch_scc0 .Lna_tb_ctx4
	s_add_u32 s1, s49, s52
	s_lshl_b32 s1, s1, 6
	s_lshl_b32 s2, s42, 11
	s_add_u32 s1, s1, s2
	s_branch .Lna_tb_done4

.Lna_tb_done4:
	s_lshl_b32 s1, s1, 15
	s_lshl_b32 s2, s43, 8
	s_add_u32 s1, s1, s2
	s_add_u32 s1, s1, 0x2000
	s_add_u32 s54, s26, s1
	s_addc_u32 s55, s27, 0
	s_add_u32 s56, s54, 0x2000
	s_addc_u32 s57, s55, 0
	global_load_dwordx4 v[96:99], v194, s[54:55]
	global_load_dwordx4 v[100:103], v194, s[56:57]
	global_load_dwordx4 v[104:107], v195, s[54:55]
	global_load_dwordx4 v[108:111], v195, s[56:57]
	s_waitcnt vmcnt(17)
	v_permlane16_swap_b32_e32 v128, v130
	v_permlane16_swap_b32_e32 v129, v131
	v_lshlrev_b32_e32 v226, 16, v128
	v_and_b32_e32 v227, 0xffff0000, v128
	v_lshlrev_b32_e32 v228, 16, v129
	v_and_b32_e32 v229, 0xffff0000, v129
	v_pk_mul_f32 v[230:231], v[226:227], s[4:5]
	v_pk_mul_f32 v[160:161], v[228:229], s[4:5]
	v_exp_f32_e32 v230, v230
	v_exp_f32_e32 v231, v231
	v_exp_f32_e32 v160, v160
	v_exp_f32_e32 v161, v161
	v_pk_mul_f32 v[32:33], v[32:33], v[226:227]
	v_pk_mul_f32 v[34:35], v[34:35], v[228:229]
	v_pk_fma_f32 v[230:231], v[230:231], v[224:225], v[224:225]
	v_pk_fma_f32 v[160:161], v[160:161], v[224:225], v[224:225]
	v_rcp_f32_e32 v230, v230
	v_rcp_f32_e32 v231, v231
	v_rcp_f32_e32 v160, v160
	v_rcp_f32_e32 v161, v161
	s_nop 0
	v_pk_mul_f32 v[32:33], v[32:33], v[230:231]
	v_pk_mul_f32 v[34:35], v[34:35], v[160:161]
	v_lshlrev_b32_e32 v226, 16, v130
	v_and_b32_e32 v227, 0xffff0000, v130
	v_lshlrev_b32_e32 v228, 16, v131
	v_and_b32_e32 v229, 0xffff0000, v131
	v_pk_mul_f32 v[230:231], v[226:227], s[4:5]
	v_pk_mul_f32 v[160:161], v[228:229], s[4:5]
	v_exp_f32_e32 v230, v230
	v_exp_f32_e32 v231, v231
	v_exp_f32_e32 v160, v160
	v_exp_f32_e32 v161, v161
	v_pk_mul_f32 v[36:37], v[36:37], v[226:227]
	v_pk_mul_f32 v[38:39], v[38:39], v[228:229]
	v_pk_fma_f32 v[230:231], v[230:231], v[224:225], v[224:225]
	v_pk_fma_f32 v[160:161], v[160:161], v[224:225], v[224:225]
	v_rcp_f32_e32 v230, v230
	v_rcp_f32_e32 v231, v231
	v_rcp_f32_e32 v160, v160
	v_rcp_f32_e32 v161, v161
	s_nop 0
	v_pk_mul_f32 v[36:37], v[36:37], v[230:231]
	v_pk_mul_f32 v[38:39], v[38:39], v[160:161]
	v_cvt_pk_bf16_f32 v32, v32, v33
	v_cvt_pk_bf16_f32 v33, v34, v35
	v_cvt_pk_bf16_f32 v34, v36, v37
	v_cvt_pk_bf16_f32 v35, v38, v39
	s_nop 1
	v_permlane16_swap_b32_e32 v32, v34
	v_permlane16_swap_b32_e32 v33, v35
	global_store_dwordx4 v212, v[32:35], s[30:31] offset:0
	v_permlane16_swap_b32_e32 v132, v134
	v_permlane16_swap_b32_e32 v133, v135
	v_lshlrev_b32_e32 v226, 16, v132
	v_and_b32_e32 v227, 0xffff0000, v132
	v_lshlrev_b32_e32 v228, 16, v133
	v_and_b32_e32 v229, 0xffff0000, v133
	v_pk_mul_f32 v[230:231], v[226:227], s[4:5]
	v_pk_mul_f32 v[160:161], v[228:229], s[4:5]
	v_exp_f32_e32 v230, v230
	v_exp_f32_e32 v231, v231
	v_exp_f32_e32 v160, v160
	v_exp_f32_e32 v161, v161
	v_pk_mul_f32 v[40:41], v[40:41], v[226:227]
	v_pk_mul_f32 v[42:43], v[42:43], v[228:229]
	v_pk_fma_f32 v[230:231], v[230:231], v[224:225], v[224:225]
	v_pk_fma_f32 v[160:161], v[160:161], v[224:225], v[224:225]
	v_rcp_f32_e32 v230, v230
	v_rcp_f32_e32 v231, v231
	v_rcp_f32_e32 v160, v160
	v_rcp_f32_e32 v161, v161
	s_nop 0
	v_pk_mul_f32 v[40:41], v[40:41], v[230:231]
	v_pk_mul_f32 v[42:43], v[42:43], v[160:161]
	v_lshlrev_b32_e32 v226, 16, v134
	v_and_b32_e32 v227, 0xffff0000, v134
	v_lshlrev_b32_e32 v228, 16, v135
	v_and_b32_e32 v229, 0xffff0000, v135
	v_pk_mul_f32 v[230:231], v[226:227], s[4:5]
	v_pk_mul_f32 v[160:161], v[228:229], s[4:5]
	v_exp_f32_e32 v230, v230
	v_exp_f32_e32 v231, v231
	v_exp_f32_e32 v160, v160
	v_exp_f32_e32 v161, v161
	v_pk_mul_f32 v[44:45], v[44:45], v[226:227]
	v_pk_mul_f32 v[46:47], v[46:47], v[228:229]
	v_pk_fma_f32 v[230:231], v[230:231], v[224:225], v[224:225]
	v_pk_fma_f32 v[160:161], v[160:161], v[224:225], v[224:225]
	v_rcp_f32_e32 v230, v230
	v_rcp_f32_e32 v231, v231
	v_rcp_f32_e32 v160, v160
	v_rcp_f32_e32 v161, v161
	s_nop 0
	v_pk_mul_f32 v[44:45], v[44:45], v[230:231]
	v_pk_mul_f32 v[46:47], v[46:47], v[160:161]
	v_cvt_pk_bf16_f32 v40, v40, v41
	v_cvt_pk_bf16_f32 v41, v42, v43
	v_cvt_pk_bf16_f32 v42, v44, v45
	v_cvt_pk_bf16_f32 v43, v46, v47
	s_nop 1
	v_permlane16_swap_b32_e32 v40, v42
	v_permlane16_swap_b32_e32 v41, v43
	global_store_dwordx4 v212, v[40:43], s[30:31] offset:64
	v_permlane16_swap_b32_e32 v136, v138
	v_permlane16_swap_b32_e32 v137, v139
	v_lshlrev_b32_e32 v226, 16, v136
	v_and_b32_e32 v227, 0xffff0000, v136
	v_lshlrev_b32_e32 v228, 16, v137
	v_and_b32_e32 v229, 0xffff0000, v137
	v_pk_mul_f32 v[230:231], v[226:227], s[4:5]
	v_pk_mul_f32 v[160:161], v[228:229], s[4:5]
	v_exp_f32_e32 v230, v230
	v_exp_f32_e32 v231, v231
	v_exp_f32_e32 v160, v160
	v_exp_f32_e32 v161, v161
	v_pk_mul_f32 v[48:49], v[48:49], v[226:227]
	v_pk_mul_f32 v[50:51], v[50:51], v[228:229]
	v_pk_fma_f32 v[230:231], v[230:231], v[224:225], v[224:225]
	v_pk_fma_f32 v[160:161], v[160:161], v[224:225], v[224:225]
	v_rcp_f32_e32 v230, v230
	v_rcp_f32_e32 v231, v231
	v_rcp_f32_e32 v160, v160
	v_rcp_f32_e32 v161, v161
	s_nop 0
	v_pk_mul_f32 v[48:49], v[48:49], v[230:231]
	v_pk_mul_f32 v[50:51], v[50:51], v[160:161]
	v_lshlrev_b32_e32 v226, 16, v138
	v_and_b32_e32 v227, 0xffff0000, v138
	v_lshlrev_b32_e32 v228, 16, v139
	v_and_b32_e32 v229, 0xffff0000, v139
	v_pk_mul_f32 v[230:231], v[226:227], s[4:5]
	v_pk_mul_f32 v[160:161], v[228:229], s[4:5]
	v_exp_f32_e32 v230, v230
	v_exp_f32_e32 v231, v231
	v_exp_f32_e32 v160, v160
	v_exp_f32_e32 v161, v161
	v_pk_mul_f32 v[52:53], v[52:53], v[226:227]
	v_pk_mul_f32 v[54:55], v[54:55], v[228:229]
	v_pk_fma_f32 v[230:231], v[230:231], v[224:225], v[224:225]
	v_pk_fma_f32 v[160:161], v[160:161], v[224:225], v[224:225]
	v_rcp_f32_e32 v230, v230
	v_rcp_f32_e32 v231, v231
	v_rcp_f32_e32 v160, v160
	v_rcp_f32_e32 v161, v161
	s_nop 0
	v_pk_mul_f32 v[52:53], v[52:53], v[230:231]
	v_pk_mul_f32 v[54:55], v[54:55], v[160:161]
	v_cvt_pk_bf16_f32 v48, v48, v49
	v_cvt_pk_bf16_f32 v49, v50, v51
	v_cvt_pk_bf16_f32 v50, v52, v53
	v_cvt_pk_bf16_f32 v51, v54, v55
	s_nop 1
	v_permlane16_swap_b32_e32 v48, v50
	v_permlane16_swap_b32_e32 v49, v51
	global_store_dwordx4 v212, v[48:51], s[30:31] offset:128
	v_permlane16_swap_b32_e32 v140, v142
	v_permlane16_swap_b32_e32 v141, v143
	v_lshlrev_b32_e32 v226, 16, v140
	v_and_b32_e32 v227, 0xffff0000, v140
	v_lshlrev_b32_e32 v228, 16, v141
	v_and_b32_e32 v229, 0xffff0000, v141
	v_pk_mul_f32 v[230:231], v[226:227], s[4:5]
	v_pk_mul_f32 v[160:161], v[228:229], s[4:5]
	v_exp_f32_e32 v230, v230
	v_exp_f32_e32 v231, v231
	v_exp_f32_e32 v160, v160
	v_exp_f32_e32 v161, v161
	v_pk_mul_f32 v[56:57], v[56:57], v[226:227]
	v_pk_mul_f32 v[58:59], v[58:59], v[228:229]
	v_pk_fma_f32 v[230:231], v[230:231], v[224:225], v[224:225]
	v_pk_fma_f32 v[160:161], v[160:161], v[224:225], v[224:225]
	v_rcp_f32_e32 v230, v230
	v_rcp_f32_e32 v231, v231
	v_rcp_f32_e32 v160, v160
	v_rcp_f32_e32 v161, v161
	s_nop 0
	v_pk_mul_f32 v[56:57], v[56:57], v[230:231]
	v_pk_mul_f32 v[58:59], v[58:59], v[160:161]
	v_lshlrev_b32_e32 v226, 16, v142
	v_and_b32_e32 v227, 0xffff0000, v142
	v_lshlrev_b32_e32 v228, 16, v143
	v_and_b32_e32 v229, 0xffff0000, v143
	v_pk_mul_f32 v[230:231], v[226:227], s[4:5]
	v_pk_mul_f32 v[160:161], v[228:229], s[4:5]
	v_exp_f32_e32 v230, v230
	v_exp_f32_e32 v231, v231
	v_exp_f32_e32 v160, v160
	v_exp_f32_e32 v161, v161
	v_pk_mul_f32 v[60:61], v[60:61], v[226:227]
	v_pk_mul_f32 v[62:63], v[62:63], v[228:229]
	v_pk_fma_f32 v[230:231], v[230:231], v[224:225], v[224:225]
	v_pk_fma_f32 v[160:161], v[160:161], v[224:225], v[224:225]
	v_rcp_f32_e32 v230, v230
	v_rcp_f32_e32 v231, v231
	v_rcp_f32_e32 v160, v160
	v_rcp_f32_e32 v161, v161
	s_nop 0
	v_pk_mul_f32 v[60:61], v[60:61], v[230:231]
	v_pk_mul_f32 v[62:63], v[62:63], v[160:161]
	v_cvt_pk_bf16_f32 v56, v56, v57
	v_cvt_pk_bf16_f32 v57, v58, v59
	v_cvt_pk_bf16_f32 v58, v60, v61
	v_cvt_pk_bf16_f32 v59, v62, v63
	s_nop 1
	v_permlane16_swap_b32_e32 v56, v58
	v_permlane16_swap_b32_e32 v57, v59
	global_store_dwordx4 v212, v[56:59], s[30:31] offset:192
	s_cmp_lt_u32 s15, s41
	s_cbranch_scc1 .Lna_unit_next
	s_branch .Lna_done
